# SwiGLU epilogue hand-written: lane rows exchanged with v_permlane16_swap, one 16-byte store per 16-row block instead of two 8-byte stores
# speedup vs baseline: 1.0189x; 1.0067x over previous
; __device__ __forceinline__ float siluf_(float x) { return x * __builtin_amdgcn_rcpf(1.f + __expf(-x)); }
;     ...
;         for (int kk = 0; kk < 2; kk++) {
;           bf16x8 af[MI], bfr[4];
;           const int csw = (((kk * 4 + fq) ^ fsw) << 3);
; #pragma unroll
;           for (int mi = 0; mi < MI; mi++) af[mi] = *(const bf16x8*)(smem + (wm * 128 + mi * 16 + fr) * 64 + csw);
; #pragma unroll
;           for (int ni = 0; ni < 4; ni++) bfr[ni] = *(const bf16x8*)(smem + 16384 + (wn * 64 + ni * 16 + fr) * 64 + csw);
; #pragma unroll
;           for (int mi = 0; mi < MI; mi++)
; #pragma unroll
;             for (int ni = 0; ni < 4; ni++)
;               acc[mi][ni] = __builtin_amdgcn_mfma_f32_16x16x32_bf16(bfr[ni], af[mi], acc[mi][ni], 0, 0, 0);
;         }
;     ...
;         } else if constexpr (EPI == EPI_SWIGLU) {
; #pragma unroll
;           for (int np = 0; np < 2; np++) {
;             const unsigned hc = ((unsigned)(n0 + wn * 64) >> 1) + np * 16 + fq * 4;
;             const f32x4 g = acc[mi][2 * np], u = acc[mi][2 * np + 1];
;             uint2 o;
;             o.x = pack2(siluf_(g[0]) * u[0], siluf_(g[1]) * u[1]);
;             o.y = pack2(siluf_(g[2]) * u[2], siluf_(g[3]) * u[3]);
;             *(uint2*)(e.b0 + (row * (unsigned)DFF + hc)) = o;
;           }
.Lsw_last:
	v_mfma_f32_16x16x32_bf16 v[134:137], v[194:197], v[156:159], v[134:137]
	v_mfma_f32_16x16x32_bf16 v[130:133], v[198:201], v[156:159], v[130:133]
	v_mfma_f32_16x16x32_bf16 v[126:129], v[202:205], v[156:159], v[126:129]
	v_mfma_f32_16x16x32_bf16 v[122:125], v[226:229], v[156:159], v[122:125]
	v_mfma_f32_16x16x32_bf16 v[118:121], v[194:197], v[166:169], v[118:121]
	v_mfma_f32_16x16x32_bf16 v[114:117], v[198:201], v[166:169], v[114:117]
	v_mfma_f32_16x16x32_bf16 v[110:113], v[202:205], v[166:169], v[110:113]
	v_mfma_f32_16x16x32_bf16 v[106:109], v[226:229], v[166:169], v[106:109]
	v_mfma_f32_16x16x32_bf16 v[102:105], v[194:197], v[170:173], v[102:105]
	v_mfma_f32_16x16x32_bf16 v[98:101], v[198:201], v[170:173], v[98:101]
	v_mfma_f32_16x16x32_bf16 v[94:97], v[202:205], v[170:173], v[94:97]
	v_mfma_f32_16x16x32_bf16 v[90:93], v[226:229], v[170:173], v[90:93]
	v_mfma_f32_16x16x32_bf16 v[86:89], v[194:197], v[174:177], v[86:89]
	v_mfma_f32_16x16x32_bf16 v[82:85], v[198:201], v[174:177], v[82:85]
	v_mfma_f32_16x16x32_bf16 v[78:81], v[202:205], v[174:177], v[78:81]
	v_mfma_f32_16x16x32_bf16 v[74:77], v[226:229], v[174:177], v[74:77]
	v_mfma_f32_16x16x32_bf16 v[70:73], v[194:197], v[178:181], v[70:73]
	v_mfma_f32_16x16x32_bf16 v[66:69], v[198:201], v[178:181], v[66:69]
	v_mfma_f32_16x16x32_bf16 v[62:65], v[202:205], v[178:181], v[62:65]
	v_mfma_f32_16x16x32_bf16 v[58:61], v[226:229], v[178:181], v[58:61]
	v_mfma_f32_16x16x32_bf16 v[54:57], v[194:197], v[182:185], v[54:57]
	v_mfma_f32_16x16x32_bf16 v[50:53], v[198:201], v[182:185], v[50:53]
	v_mfma_f32_16x16x32_bf16 v[46:49], v[202:205], v[182:185], v[46:49]
	v_mfma_f32_16x16x32_bf16 v[42:45], v[226:229], v[182:185], v[42:45]
	v_mfma_f32_16x16x32_bf16 v[38:41], v[194:197], v[186:189], v[38:41]
	v_mfma_f32_16x16x32_bf16 v[34:37], v[198:201], v[186:189], v[34:37]
	v_mfma_f32_16x16x32_bf16 v[30:33], v[202:205], v[186:189], v[30:33]
	v_mfma_f32_16x16x32_bf16 v[26:29], v[226:229], v[186:189], v[26:29]
	v_mfma_f32_16x16x32_bf16 v[22:25], v[194:197], v[190:193], v[22:25]
	v_mfma_f32_16x16x32_bf16 v[18:21], v[198:201], v[190:193], v[18:21]
	v_mfma_f32_16x16x32_bf16 v[14:17], v[202:205], v[190:193], v[14:17]
	v_mfma_f32_16x16x32_bf16 v[10:13], v[226:229], v[190:193], v[10:13]
	v_or_b32_e32 v8, s8, v148
	v_lshrrev_b32_e32 v8, 1, v8
	v_add_u32_e32 v142, s7, v150
	v_or_b32_e32 v8, v8, v149
	s_movk_i32 s4, 0xb00
	v_mad_u64_u32 v[142:143], s[4:5], v142, s4, v[8:9]
	v_bfe_u32 v144, v2, 4, 1
	v_mul_u32_u24_e32 v144, 12, v144
	s_nop 0
	v_add_u32_e32 v142, v142, v144
	v_mul_f32_e32 v174, 0xbfb8aa3b, v134
	v_mul_f32_e32 v175, 0xbfb8aa3b, v135
	v_mul_f32_e32 v176, 0xbfb8aa3b, v136
	v_mul_f32_e32 v177, 0xbfb8aa3b, v137
	v_mul_f32_e32 v178, 0xbfb8aa3b, v126
	v_mul_f32_e32 v179, 0xbfb8aa3b, v127
	v_mul_f32_e32 v180, 0xbfb8aa3b, v128
	v_mul_f32_e32 v181, 0xbfb8aa3b, v129
	v_exp_f32_e32 v174, v174
	v_exp_f32_e32 v175, v175
	v_exp_f32_e32 v176, v176
	v_exp_f32_e32 v177, v177
	v_exp_f32_e32 v178, v178
	v_exp_f32_e32 v179, v179
	v_exp_f32_e32 v180, v180
	v_exp_f32_e32 v181, v181
	v_add_f32_e32 v174, 1.0, v174
	v_add_f32_e32 v175, 1.0, v175
	v_add_f32_e32 v176, 1.0, v176
	v_add_f32_e32 v177, 1.0, v177
	v_add_f32_e32 v178, 1.0, v178
	v_add_f32_e32 v179, 1.0, v179
	v_add_f32_e32 v180, 1.0, v180
	v_add_f32_e32 v181, 1.0, v181
	v_rcp_f32_e32 v174, v174
	v_rcp_f32_e32 v175, v175
	v_rcp_f32_e32 v176, v176
	v_rcp_f32_e32 v177, v177
	v_rcp_f32_e32 v178, v178
	v_rcp_f32_e32 v179, v179
	v_rcp_f32_e32 v180, v180
	v_rcp_f32_e32 v181, v181
	v_mov_b32_e32 v8, v142
	v_pk_mul_f32 v[134:135], v[134:135], v[174:175]
	v_pk_mul_f32 v[136:137], v[136:137], v[176:177]
	v_pk_mul_f32 v[126:127], v[126:127], v[178:179]
	v_pk_mul_f32 v[128:129], v[128:129], v[180:181]
	v_lshl_add_u64 v[182:183], v[8:9], 1, s[52:53]
	v_pk_mul_f32 v[130:131], v[130:131], v[134:135]
	v_pk_mul_f32 v[132:133], v[132:133], v[136:137]
	v_pk_mul_f32 v[122:123], v[122:123], v[126:127]
	v_pk_mul_f32 v[124:125], v[124:125], v[128:129]
	v_cvt_pk_bf16_f32 v166, v130, v131
	v_cvt_pk_bf16_f32 v167, v132, v133
	v_cvt_pk_bf16_f32 v168, v122, v123
	v_cvt_pk_bf16_f32 v169, v124, v125
	s_nop 1
	v_permlane16_swap_b32 v166, v168
	v_permlane16_swap_b32 v167, v169
	s_nop 1
	global_store_dwordx4 v[182:183], v[166:169], off
	v_mul_f32_e32 v174, 0xbfb8aa3b, v118
	v_mul_f32_e32 v175, 0xbfb8aa3b, v119
	v_mul_f32_e32 v176, 0xbfb8aa3b, v120
	v_mul_f32_e32 v177, 0xbfb8aa3b, v121
	v_mul_f32_e32 v178, 0xbfb8aa3b, v110
	v_mul_f32_e32 v179, 0xbfb8aa3b, v111
	v_mul_f32_e32 v180, 0xbfb8aa3b, v112
	v_mul_f32_e32 v181, 0xbfb8aa3b, v113
	v_exp_f32_e32 v174, v174
	v_exp_f32_e32 v175, v175
	v_exp_f32_e32 v176, v176
	v_exp_f32_e32 v177, v177
	v_exp_f32_e32 v178, v178
	v_exp_f32_e32 v179, v179
	v_exp_f32_e32 v180, v180
	v_exp_f32_e32 v181, v181
	v_add_f32_e32 v174, 1.0, v174
	v_add_f32_e32 v175, 1.0, v175
	v_add_f32_e32 v176, 1.0, v176
	v_add_f32_e32 v177, 1.0, v177
	v_add_f32_e32 v178, 1.0, v178
	v_add_f32_e32 v179, 1.0, v179
	v_add_f32_e32 v180, 1.0, v180
	v_add_f32_e32 v181, 1.0, v181
	v_rcp_f32_e32 v174, v174
	v_rcp_f32_e32 v175, v175
	v_rcp_f32_e32 v176, v176
	v_rcp_f32_e32 v177, v177
	v_rcp_f32_e32 v178, v178
	v_rcp_f32_e32 v179, v179
	v_rcp_f32_e32 v180, v180
	v_rcp_f32_e32 v181, v181
	v_add_u32_e32 v8, 0xb000, v142
	v_pk_mul_f32 v[118:119], v[118:119], v[174:175]
	v_pk_mul_f32 v[120:121], v[120:121], v[176:177]
	v_pk_mul_f32 v[110:111], v[110:111], v[178:179]
	v_pk_mul_f32 v[112:113], v[112:113], v[180:181]
	v_lshl_add_u64 v[184:185], v[8:9], 1, s[52:53]
	v_pk_mul_f32 v[114:115], v[114:115], v[118:119]
	v_pk_mul_f32 v[116:117], v[116:117], v[120:121]
	v_pk_mul_f32 v[106:107], v[106:107], v[110:111]
; __device__ __forceinline__ float siluf_(float x) { return x * __builtin_amdgcn_rcpf(1.f + __expf(-x)); }
;     ...
;         } else if constexpr (EPI == EPI_SWIGLU) {
; #pragma unroll
;           for (int np = 0; np < 2; np++) {
;             const unsigned hc = ((unsigned)(n0 + wn * 64) >> 1) + np * 16 + fq * 4;
;             const f32x4 g = acc[mi][2 * np], u = acc[mi][2 * np + 1];
;             uint2 o;
;             o.x = pack2(siluf_(g[0]) * u[0], siluf_(g[1]) * u[1]);
;             o.y = pack2(siluf_(g[2]) * u[2], siluf_(g[3]) * u[3]);
;             *(uint2*)(e.b0 + (row * (unsigned)DFF + hc)) = o;
;           }
	v_pk_mul_f32 v[108:109], v[108:109], v[112:113]
	v_cvt_pk_bf16_f32 v170, v114, v115
	v_cvt_pk_bf16_f32 v171, v116, v117
	v_cvt_pk_bf16_f32 v172, v106, v107
	v_cvt_pk_bf16_f32 v173, v108, v109
	s_nop 1
	v_permlane16_swap_b32 v170, v172
	v_permlane16_swap_b32 v171, v173
	s_nop 1
	global_store_dwordx4 v[184:185], v[170:173], off
	v_mul_f32_e32 v174, 0xbfb8aa3b, v102
	v_mul_f32_e32 v175, 0xbfb8aa3b, v103
	v_mul_f32_e32 v176, 0xbfb8aa3b, v104
	v_mul_f32_e32 v177, 0xbfb8aa3b, v105
	v_mul_f32_e32 v178, 0xbfb8aa3b, v94
	v_mul_f32_e32 v179, 0xbfb8aa3b, v95
	v_mul_f32_e32 v180, 0xbfb8aa3b, v96
	v_mul_f32_e32 v181, 0xbfb8aa3b, v97
	v_exp_f32_e32 v174, v174
	v_exp_f32_e32 v175, v175
	v_exp_f32_e32 v176, v176
	v_exp_f32_e32 v177, v177
	v_exp_f32_e32 v178, v178
	v_exp_f32_e32 v179, v179
	v_exp_f32_e32 v180, v180
	v_exp_f32_e32 v181, v181
	v_add_f32_e32 v174, 1.0, v174
	v_add_f32_e32 v175, 1.0, v175
	v_add_f32_e32 v176, 1.0, v176
	v_add_f32_e32 v177, 1.0, v177
	v_add_f32_e32 v178, 1.0, v178
	v_add_f32_e32 v179, 1.0, v179
	v_add_f32_e32 v180, 1.0, v180
	v_add_f32_e32 v181, 1.0, v181
	v_rcp_f32_e32 v174, v174
	v_rcp_f32_e32 v175, v175
	v_rcp_f32_e32 v176, v176
	v_rcp_f32_e32 v177, v177
	v_rcp_f32_e32 v178, v178
	v_rcp_f32_e32 v179, v179
	v_rcp_f32_e32 v180, v180
	v_rcp_f32_e32 v181, v181
	v_add_u32_e32 v8, 0x16000, v142
	v_pk_mul_f32 v[102:103], v[102:103], v[174:175]
	v_pk_mul_f32 v[104:105], v[104:105], v[176:177]
	v_pk_mul_f32 v[94:95], v[94:95], v[178:179]
	v_pk_mul_f32 v[96:97], v[96:97], v[180:181]
	v_lshl_add_u64 v[182:183], v[8:9], 1, s[52:53]
	v_pk_mul_f32 v[98:99], v[98:99], v[102:103]
	v_pk_mul_f32 v[100:101], v[100:101], v[104:105]
	v_pk_mul_f32 v[90:91], v[90:91], v[94:95]
	v_pk_mul_f32 v[92:93], v[92:93], v[96:97]
	v_cvt_pk_bf16_f32 v166, v98, v99
	v_cvt_pk_bf16_f32 v167, v100, v101
	v_cvt_pk_bf16_f32 v168, v90, v91
	v_cvt_pk_bf16_f32 v169, v92, v93
	s_nop 1
	v_permlane16_swap_b32 v166, v168
	v_permlane16_swap_b32 v167, v169
	s_nop 1
	global_store_dwordx4 v[182:183], v[166:169], off
	v_mul_f32_e32 v174, 0xbfb8aa3b, v86
	v_mul_f32_e32 v175, 0xbfb8aa3b, v87
	v_mul_f32_e32 v176, 0xbfb8aa3b, v88
	v_mul_f32_e32 v177, 0xbfb8aa3b, v89
	v_mul_f32_e32 v178, 0xbfb8aa3b, v78
	v_mul_f32_e32 v179, 0xbfb8aa3b, v79
	v_mul_f32_e32 v180, 0xbfb8aa3b, v80
	v_mul_f32_e32 v181, 0xbfb8aa3b, v81
	v_exp_f32_e32 v174, v174
	v_exp_f32_e32 v175, v175
	v_exp_f32_e32 v176, v176
	v_exp_f32_e32 v177, v177
	v_exp_f32_e32 v178, v178
	v_exp_f32_e32 v179, v179
	v_exp_f32_e32 v180, v180
	v_exp_f32_e32 v181, v181
	v_add_f32_e32 v174, 1.0, v174
	v_add_f32_e32 v175, 1.0, v175
	v_add_f32_e32 v176, 1.0, v176
	v_add_f32_e32 v177, 1.0, v177
	v_add_f32_e32 v178, 1.0, v178
	v_add_f32_e32 v179, 1.0, v179
	v_add_f32_e32 v180, 1.0, v180
	v_add_f32_e32 v181, 1.0, v181
	v_rcp_f32_e32 v174, v174
	v_rcp_f32_e32 v175, v175
	v_rcp_f32_e32 v176, v176
	v_rcp_f32_e32 v177, v177
	v_rcp_f32_e32 v178, v178
	v_rcp_f32_e32 v179, v179
	v_rcp_f32_e32 v180, v180
	v_rcp_f32_e32 v181, v181
	v_add_u32_e32 v8, 0x21000, v142
	v_pk_mul_f32 v[86:87], v[86:87], v[174:175]
	v_pk_mul_f32 v[88:89], v[88:89], v[176:177]
	v_pk_mul_f32 v[78:79], v[78:79], v[178:179]
	v_pk_mul_f32 v[80:81], v[80:81], v[180:181]
	v_lshl_add_u64 v[184:185], v[8:9], 1, s[52:53]
	v_pk_mul_f32 v[82:83], v[82:83], v[86:87]
	v_pk_mul_f32 v[84:85], v[84:85], v[88:89]
	v_pk_mul_f32 v[74:75], v[74:75], v[78:79]
	v_pk_mul_f32 v[76:77], v[76:77], v[80:81]
	v_cvt_pk_bf16_f32 v170, v82, v83
	v_cvt_pk_bf16_f32 v171, v84, v85
	v_cvt_pk_bf16_f32 v172, v74, v75
	v_cvt_pk_bf16_f32 v173, v76, v77
	s_nop 1
	v_permlane16_swap_b32 v170, v172
	v_permlane16_swap_b32 v171, v173
	s_nop 1
	global_store_dwordx4 v[184:185], v[170:173], off
	v_mul_f32_e32 v174, 0xbfb8aa3b, v70
	v_mul_f32_e32 v175, 0xbfb8aa3b, v71
	v_mul_f32_e32 v176, 0xbfb8aa3b, v72
	v_mul_f32_e32 v177, 0xbfb8aa3b, v73
	v_mul_f32_e32 v178, 0xbfb8aa3b, v62
	v_mul_f32_e32 v179, 0xbfb8aa3b, v63
	v_mul_f32_e32 v180, 0xbfb8aa3b, v64
	v_mul_f32_e32 v181, 0xbfb8aa3b, v65
	v_exp_f32_e32 v174, v174
	v_exp_f32_e32 v175, v175
	v_exp_f32_e32 v176, v176
	v_exp_f32_e32 v177, v177
	v_exp_f32_e32 v178, v178
	v_exp_f32_e32 v179, v179
	v_exp_f32_e32 v180, v180
	v_exp_f32_e32 v181, v181
	v_add_f32_e32 v174, 1.0, v174
	v_add_f32_e32 v175, 1.0, v175
	v_add_f32_e32 v176, 1.0, v176
	v_add_f32_e32 v177, 1.0, v177
	v_add_f32_e32 v178, 1.0, v178
	v_add_f32_e32 v179, 1.0, v179
	v_add_f32_e32 v180, 1.0, v180
	v_add_f32_e32 v181, 1.0, v181
	v_rcp_f32_e32 v174, v174
	v_rcp_f32_e32 v175, v175
	v_rcp_f32_e32 v176, v176
	v_rcp_f32_e32 v177, v177
	v_rcp_f32_e32 v178, v178
	v_rcp_f32_e32 v179, v179
	v_rcp_f32_e32 v180, v180
	v_rcp_f32_e32 v181, v181
	v_add_u32_e32 v8, 0x2c000, v142
	v_pk_mul_f32 v[70:71], v[70:71], v[174:175]
	v_pk_mul_f32 v[72:73], v[72:73], v[176:177]
	v_pk_mul_f32 v[62:63], v[62:63], v[178:179]
	v_pk_mul_f32 v[64:65], v[64:65], v[180:181]
	v_lshl_add_u64 v[182:183], v[8:9], 1, s[52:53]
	v_pk_mul_f32 v[66:67], v[66:67], v[70:71]
	v_pk_mul_f32 v[68:69], v[68:69], v[72:73]
	v_pk_mul_f32 v[58:59], v[58:59], v[62:63]
	v_pk_mul_f32 v[60:61], v[60:61], v[64:65]
	v_cvt_pk_bf16_f32 v166, v66, v67
	v_cvt_pk_bf16_f32 v167, v68, v69
	v_cvt_pk_bf16_f32 v168, v58, v59
	v_cvt_pk_bf16_f32 v169, v60, v61
; __device__ __forceinline__ float siluf_(float x) { return x * __builtin_amdgcn_rcpf(1.f + __expf(-x)); }
;     ...
;         } else if constexpr (EPI == EPI_SWIGLU) {
; #pragma unroll
;           for (int np = 0; np < 2; np++) {
;             const unsigned hc = ((unsigned)(n0 + wn * 64) >> 1) + np * 16 + fq * 4;
;             const f32x4 g = acc[mi][2 * np], u = acc[mi][2 * np + 1];
;             uint2 o;
;             o.x = pack2(siluf_(g[0]) * u[0], siluf_(g[1]) * u[1]);
;             o.y = pack2(siluf_(g[2]) * u[2], siluf_(g[3]) * u[3]);
;             *(uint2*)(e.b0 + (row * (unsigned)DFF + hc)) = o;
;           }
	s_nop 1
	v_permlane16_swap_b32 v166, v168
	v_permlane16_swap_b32 v167, v169
	s_nop 1
	global_store_dwordx4 v[182:183], v[166:169], off
	v_mul_f32_e32 v174, 0xbfb8aa3b, v54
	v_mul_f32_e32 v175, 0xbfb8aa3b, v55
	v_mul_f32_e32 v176, 0xbfb8aa3b, v56
	v_mul_f32_e32 v177, 0xbfb8aa3b, v57
	v_mul_f32_e32 v178, 0xbfb8aa3b, v46
	v_mul_f32_e32 v179, 0xbfb8aa3b, v47
	v_mul_f32_e32 v180, 0xbfb8aa3b, v48
	v_mul_f32_e32 v181, 0xbfb8aa3b, v49
	v_exp_f32_e32 v174, v174
	v_exp_f32_e32 v175, v175
	v_exp_f32_e32 v176, v176
	v_exp_f32_e32 v177, v177
	v_exp_f32_e32 v178, v178
	v_exp_f32_e32 v179, v179
	v_exp_f32_e32 v180, v180
	v_exp_f32_e32 v181, v181
	v_add_f32_e32 v174, 1.0, v174
	v_add_f32_e32 v175, 1.0, v175
	v_add_f32_e32 v176, 1.0, v176
	v_add_f32_e32 v177, 1.0, v177
	v_add_f32_e32 v178, 1.0, v178
	v_add_f32_e32 v179, 1.0, v179
	v_add_f32_e32 v180, 1.0, v180
	v_add_f32_e32 v181, 1.0, v181
	v_rcp_f32_e32 v174, v174
	v_rcp_f32_e32 v175, v175
	v_rcp_f32_e32 v176, v176
	v_rcp_f32_e32 v177, v177
	v_rcp_f32_e32 v178, v178
	v_rcp_f32_e32 v179, v179
	v_rcp_f32_e32 v180, v180
	v_rcp_f32_e32 v181, v181
	v_add_u32_e32 v8, 0x37000, v142
	v_pk_mul_f32 v[54:55], v[54:55], v[174:175]
	v_pk_mul_f32 v[56:57], v[56:57], v[176:177]
	v_pk_mul_f32 v[46:47], v[46:47], v[178:179]
	v_pk_mul_f32 v[48:49], v[48:49], v[180:181]
	v_lshl_add_u64 v[184:185], v[8:9], 1, s[52:53]
	v_pk_mul_f32 v[50:51], v[50:51], v[54:55]
	v_pk_mul_f32 v[52:53], v[52:53], v[56:57]
	v_pk_mul_f32 v[42:43], v[42:43], v[46:47]
	v_pk_mul_f32 v[44:45], v[44:45], v[48:49]
	v_cvt_pk_bf16_f32 v170, v50, v51
	v_cvt_pk_bf16_f32 v171, v52, v53
	v_cvt_pk_bf16_f32 v172, v42, v43
	v_cvt_pk_bf16_f32 v173, v44, v45
	s_nop 1
	v_permlane16_swap_b32 v170, v172
	v_permlane16_swap_b32 v171, v173
	s_nop 1
	global_store_dwordx4 v[184:185], v[170:173], off
	v_mul_f32_e32 v174, 0xbfb8aa3b, v38
	v_mul_f32_e32 v175, 0xbfb8aa3b, v39
	v_mul_f32_e32 v176, 0xbfb8aa3b, v40
	v_mul_f32_e32 v177, 0xbfb8aa3b, v41
	v_mul_f32_e32 v178, 0xbfb8aa3b, v30
	v_mul_f32_e32 v179, 0xbfb8aa3b, v31
	v_mul_f32_e32 v180, 0xbfb8aa3b, v32
	v_mul_f32_e32 v181, 0xbfb8aa3b, v33
	v_exp_f32_e32 v174, v174
	v_exp_f32_e32 v175, v175
	v_exp_f32_e32 v176, v176
	v_exp_f32_e32 v177, v177
	v_exp_f32_e32 v178, v178
	v_exp_f32_e32 v179, v179
	v_exp_f32_e32 v180, v180
	v_exp_f32_e32 v181, v181
	v_add_f32_e32 v174, 1.0, v174
	v_add_f32_e32 v175, 1.0, v175
	v_add_f32_e32 v176, 1.0, v176
	v_add_f32_e32 v177, 1.0, v177
	v_add_f32_e32 v178, 1.0, v178
	v_add_f32_e32 v179, 1.0, v179
	v_add_f32_e32 v180, 1.0, v180
	v_add_f32_e32 v181, 1.0, v181
	v_rcp_f32_e32 v174, v174
	v_rcp_f32_e32 v175, v175
	v_rcp_f32_e32 v176, v176
	v_rcp_f32_e32 v177, v177
	v_rcp_f32_e32 v178, v178
	v_rcp_f32_e32 v179, v179
	v_rcp_f32_e32 v180, v180
	v_rcp_f32_e32 v181, v181
	v_add_u32_e32 v8, 0x42000, v142
	v_pk_mul_f32 v[38:39], v[38:39], v[174:175]
	v_pk_mul_f32 v[40:41], v[40:41], v[176:177]
	v_pk_mul_f32 v[30:31], v[30:31], v[178:179]
	v_pk_mul_f32 v[32:33], v[32:33], v[180:181]
	v_lshl_add_u64 v[182:183], v[8:9], 1, s[52:53]
	v_pk_mul_f32 v[34:35], v[34:35], v[38:39]
	v_pk_mul_f32 v[36:37], v[36:37], v[40:41]
	v_pk_mul_f32 v[26:27], v[26:27], v[30:31]
	v_pk_mul_f32 v[28:29], v[28:29], v[32:33]
	v_cvt_pk_bf16_f32 v166, v34, v35
	v_cvt_pk_bf16_f32 v167, v36, v37
	v_cvt_pk_bf16_f32 v168, v26, v27
	v_cvt_pk_bf16_f32 v169, v28, v29
	s_nop 1
	v_permlane16_swap_b32 v166, v168
	v_permlane16_swap_b32 v167, v169
	s_nop 1
	global_store_dwordx4 v[182:183], v[166:169], off
	v_mul_f32_e32 v174, 0xbfb8aa3b, v22
	v_mul_f32_e32 v175, 0xbfb8aa3b, v23
	v_mul_f32_e32 v176, 0xbfb8aa3b, v24
	v_mul_f32_e32 v177, 0xbfb8aa3b, v25
	v_mul_f32_e32 v178, 0xbfb8aa3b, v14
	v_mul_f32_e32 v179, 0xbfb8aa3b, v15
	v_mul_f32_e32 v180, 0xbfb8aa3b, v16
	v_mul_f32_e32 v181, 0xbfb8aa3b, v17
	v_exp_f32_e32 v174, v174
	v_exp_f32_e32 v175, v175
	v_exp_f32_e32 v176, v176
	v_exp_f32_e32 v177, v177
	v_exp_f32_e32 v178, v178
	v_exp_f32_e32 v179, v179
	v_exp_f32_e32 v180, v180
	v_exp_f32_e32 v181, v181
	v_add_f32_e32 v174, 1.0, v174
	v_add_f32_e32 v175, 1.0, v175
	v_add_f32_e32 v176, 1.0, v176
	v_add_f32_e32 v177, 1.0, v177
	v_add_f32_e32 v178, 1.0, v178
	v_add_f32_e32 v179, 1.0, v179
	v_add_f32_e32 v180, 1.0, v180
	v_add_f32_e32 v181, 1.0, v181
	v_rcp_f32_e32 v174, v174
	v_rcp_f32_e32 v175, v175
	v_rcp_f32_e32 v176, v176
	v_rcp_f32_e32 v177, v177
	v_rcp_f32_e32 v178, v178
	v_rcp_f32_e32 v179, v179
	v_rcp_f32_e32 v180, v180
	v_rcp_f32_e32 v181, v181
	v_add_u32_e32 v8, 0x4d000, v142
	v_pk_mul_f32 v[22:23], v[22:23], v[174:175]
	v_pk_mul_f32 v[24:25], v[24:25], v[176:177]
	v_pk_mul_f32 v[14:15], v[14:15], v[178:179]
	v_pk_mul_f32 v[16:17], v[16:17], v[180:181]
	v_lshl_add_u64 v[184:185], v[8:9], 1, s[52:53]
	v_pk_mul_f32 v[18:19], v[18:19], v[22:23]
	v_pk_mul_f32 v[20:21], v[20:21], v[24:25]
	v_pk_mul_f32 v[10:11], v[10:11], v[14:15]
	v_pk_mul_f32 v[12:13], v[12:13], v[16:17]
	v_cvt_pk_bf16_f32 v170, v18, v19
	v_cvt_pk_bf16_f32 v171, v20, v21
	v_cvt_pk_bf16_f32 v172, v10, v11
	v_cvt_pk_bf16_f32 v173, v12, v13
	s_nop 1
	v_permlane16_swap_b32 v170, v172
	v_permlane16_swap_b32 v171, v173
	s_nop 1
	global_store_dwordx4 v[184:185], v[170:173], off
	s_add_i32 s6, s6, 1
	s_mov_b64 s[4:5], 0
	s_branch .LBB0_2615
